# work queue: first item per workgroup assigned statically (item = workgroup id), dynamic claims offset by grid size; removes the 256-way contended atomic burst after gla_item
# speedup vs baseline: 1.0035x; 1.0035x over previous
; #define LAS __attribute__((address_space(3)))
; __device__ __forceinline__ int next_item(unsigned* ctr, LAS unsigned char* lds) {
;     __syncthreads();
;     if (threadIdx.x == 0) *(LAS unsigned*)(lds + LDS_SLOT) = atomicAdd(ctr, 1u);
;     __syncthreads();
;     return (int)*(LAS unsigned*)(lds + LDS_SLOT);
; }
; __device__ void phase_branches(const Params& P, int l, int half, LAS unsigned char* lds) {
;     unsigned* ctr = (unsigned*)(P.ws + WS_CTL) + 64 * (l * 2 + half);
;     for (int it = blockIdx.x; it < 256; it += gridDim.x) gla_item(P, l, it >> 5, (it >> 3) & 3, it & 7, lds);
;     int it = next_item(ctr, lds);
.LBB0_510:
	v_readlane_b32 s0, v255, 29
	v_readlane_b32 s1, v255, 30
	s_lshl_b32 s2, s0, 7
	v_readlane_b32 s0, v255, 32
	v_readlane_b32 s1, v255, 33
	s_and_b64 s[0:1], s[0:1], exec
	s_cselect_b32 s0, 64, 0
	s_or_b32 s0, s0, s2
	s_ashr_i32 s1, s0, 31
	s_lshl_b64 s[0:1], s[0:1], 2
	s_add_u32 s0, s74, s0
	s_addc_u32 s1, s75, s1
	s_waitcnt lgkmcnt(0)
	s_barrier
	s_mov_b64 s[30:31], exec
	v_readlane_b32 s4, v251, 8
	v_readlane_b32 s5, v251, 9
	s_and_b64 s[4:5], s[30:31], s[4:5]
	v_readlane_b32 s81, v255, 19
	s_mov_b64 exec, s[4:5]
	s_cbranch_execz .LBB0_514
	s_waitcnt vmcnt(4)
	v_mov_b32_e32 v2, s81
	v_readlane_b32 s2, v255, 15
	s_nop 1
	v_mov_b32_e32 v3, s2
	ds_write_b32 v3, v2

; #define LAS __attribute__((address_space(3)))
; __device__ __forceinline__ int next_item(unsigned* ctr, LAS unsigned char* lds) {
;     __syncthreads();
;     if (threadIdx.x == 0) *(LAS unsigned*)(lds + LDS_SLOT) = atomicAdd(ctr, 1u);
;     __syncthreads();
;     return (int)*(LAS unsigned*)(lds + LDS_SLOT);
; __device__ void phase_branches(const Params& P, int l, int half, LAS unsigned char* lds) {
;     ...
;         else { sc_item(P, l, it - 1536); it = next_item(ctr, lds); }
.LBB0_526:
	s_or_b64 exec, exec, s[36:37]
	s_waitcnt vmcnt(0)
	v_readfirstlane_b32 s4, v3
	s_nop 1
	v_add_u32_e32 v2, s4, v2
	v_add_u32_e32 v2, s94, v2
	v_readlane_b32 s4, v255, 15
	s_nop 1
	v_mov_b32_e32 v3, s4
	ds_write_b32 v3, v2

; __device__ __forceinline__ void attn_item(const Params& P, int half, int item, LAS unsigned char* lds, unsigned* ctr) {
;     ...
;     unsigned nxt_id = 0u;
;     if (tid == 0) nxt_id = atomicAdd(ctr, 1u);
.LBB0_538:
	s_or_b64 exec, exec, s[40:41]
	s_waitcnt vmcnt(0)
	v_readfirstlane_b32 s7, v19
	s_nop 1
	v_add_u32_e32 v135, s7, v18
	v_add_u32_e32 v135, s94, v135
